# in-proj bf16 epilogue stores: lanes transposed through ds_bpermute so that 4 adjacent lanes write 64 contiguous bytes of one row (data and address pulled from the same source lane)
# baseline (speedup 1.0000x reference)
.LBB0_701:
	v_mbcnt_lo_u32_b32 v142, -1, 0
	v_mbcnt_hi_u32_b32 v142, -1, v142
	v_and_b32_e32 v143, 3, v142
	v_and_b32_e32 v142, 60, v142
	v_lshl_or_b32 v252, v143, 6, v142
	v_lshl_add_u32 v142, s54, 8, v174
	v_ashrrev_i32_e32 v143, 31, v142
	v_lshl_add_u64 v[140:141], v[142:143], 3, s[2:3]
	global_load_dwordx2 v[158:159], v[140:141], off
	global_load_dwordx2 v[156:157], v[140:141], off offset:128
	global_load_dwordx2 v[154:155], v[140:141], off offset:256
	global_load_dwordx2 v[152:153], v[140:141], off offset:384
	global_load_dwordx2 v[150:151], v[140:141], off offset:1024
	global_load_dwordx2 v[148:149], v[140:141], off offset:1152
	global_load_dwordx2 v[146:147], v[140:141], off offset:1280
	global_load_dwordx2 v[144:145], v[140:141], off offset:1408
	s_cmp_gt_i32 s42, 13
	s_cselect_b64 s[0:1], -1, 0
	s_cmp_lt_i32 s42, 14
	s_cselect_b64 s[6:7], -1, 0
	s_and_b64 vcc, s[6:7], exec
	s_cselect_b32 s6, 0, -14
	s_movk_i32 s7, 0xe00
	s_mov_b32 s34, 0x800000
	s_cselect_b32 s25, s18, s31
	s_cselect_b32 s28, s17, s30
	s_cselect_b32 s24, s7, 0xc00
	s_add_i32 s6, s6, s42
	v_lshl_or_b32 v140, s6, 8, v176
	v_ashrrev_i32_e32 v141, 31, v140
	s_mov_b64 s[6:7], -1
	s_waitcnt vmcnt(0)
	v_ffbh_u32_e32 v143, v159
	v_min_u32_e32 v143, 32, v143
	v_lshlrev_b64 v[158:159], v143, v[158:159]
	v_min_u32_e32 v158, 1, v158
	v_or_b32_e32 v158, v159, v158
	v_cvt_f32_u32_e32 v158, v158
	v_sub_u32_e32 v143, 32, v143
	v_ldexp_f32 v143, v158, v143
	v_fmamk_f32 v143, v143, 0x2e800000, v210
	s_nop 0
	v_rsq_f32_e32 v143, v143
	s_nop 0
	s_nop 0
	v_mov_b32_e32 v158, v143
	v_pk_mul_f32 v[128:129], v[128:129], v[158:159] op_sel_hi:[1,0]
	v_pk_mul_f32 v[170:171], v[126:127], v[158:159] op_sel_hi:[1,0]
	v_pk_mul_f32 v[124:125], v[124:125], v[158:159] op_sel_hi:[1,0]
	v_pk_mul_f32 v[126:127], v[122:123], v[158:159] op_sel_hi:[1,0]
	s_cbranch_vccnz .LBB0_703
	s_mov_b32 s98, 0xbfb8aa3b
	s_mov_b32 s32, 0x437f0000
	v_pk_mul_f32 v[170:171], v[170:171], s[98:99] op_sel_hi:[1,0]
	v_pk_mul_f32 v[128:129], v[128:129], s[98:99] op_sel_hi:[1,0]
	v_pk_mul_f32 v[126:127], v[126:127], s[98:99] op_sel_hi:[1,0]
	v_pk_mul_f32 v[124:125], v[124:125], s[98:99] op_sel_hi:[1,0]
	v_exp_f32_e32 v170, v170
	v_exp_f32_e32 v171, v171
	v_exp_f32_e32 v128, v128
	v_exp_f32_e32 v129, v129
	v_exp_f32_e32 v126, v126
	v_exp_f32_e32 v127, v127
	v_exp_f32_e32 v124, v124
	v_exp_f32_e32 v125, v125
	v_pk_add_f32 v[170:171], v[170:171], 1.0 op_sel_hi:[1,0]
	v_pk_add_f32 v[128:129], v[128:129], 1.0 op_sel_hi:[1,0]
	v_pk_add_f32 v[126:127], v[126:127], 1.0 op_sel_hi:[1,0]
	v_pk_add_f32 v[124:125], v[124:125], 1.0 op_sel_hi:[1,0]
	v_rcp_f32_e32 v170, v170
	v_rcp_f32_e32 v171, v171
	v_rcp_f32_e32 v128, v128
	v_rcp_f32_e32 v129, v129
	v_rcp_f32_e32 v126, v126
	v_rcp_f32_e32 v127, v127
	v_rcp_f32_e32 v124, v124
	v_rcp_f32_e32 v125, v125
	v_pk_mul_f32 v[170:171], v[170:171], s[32:33] op_sel_hi:[1,0]
	v_pk_mul_f32 v[128:129], v[128:129], s[32:33] op_sel_hi:[1,0]
	v_pk_mul_f32 v[126:127], v[126:127], s[32:33] op_sel_hi:[1,0]
	v_pk_mul_f32 v[124:125], v[124:125], s[32:33] op_sel_hi:[1,0]
	v_max_f32_e32 v170, 1.0, v170
	v_max_f32_e32 v171, 1.0, v171
	v_max_f32_e32 v128, 1.0, v128
	v_max_f32_e32 v129, 1.0, v129
	v_max_f32_e32 v126, 1.0, v126
	v_max_f32_e32 v127, 1.0, v127
	v_max_f32_e32 v124, 1.0, v124
	v_max_f32_e32 v125, 1.0, v125
	v_rndne_f32_e32 v170, v170
	v_rndne_f32_e32 v171, v171
	v_rndne_f32_e32 v128, v128
	v_rndne_f32_e32 v129, v129
	v_rndne_f32_e32 v126, v126
	v_rndne_f32_e32 v127, v127
	v_rndne_f32_e32 v124, v124
	v_rndne_f32_e32 v125, v125
	v_cvt_pk_u8_f32 v122, v170, 0, 0
	v_cvt_pk_u8_f32 v122, v171, 1, v122
	v_cvt_pk_u8_f32 v123, v126, 0, 0
	v_cvt_pk_u8_f32 v123, v127, 1, v123
	v_cvt_pk_u8_f32 v122, v128, 2, v122
	v_cvt_pk_u8_f32 v122, v129, 3, v122
	v_cvt_pk_u8_f32 v123, v124, 2, v123
	v_cvt_pk_u8_f32 v123, v125, 3, v123
	v_mov_b64_e32 v[172:173], s[30:31]
	v_mad_i64_i32 v[172:173], s[6:7], v142, s55, v[172:173]
	v_lshl_add_u64 v[172:173], v[172:173], 0, v[140:141]
	s_mov_b64 s[6:7], 0
	v_mov_b32_e32 v246, v122
	v_mov_b32_e32 v247, v123
.LBB0_703:
	v_mov_b32_e32 v122, s28
	v_mov_b32_e32 v123, s25
	v_lshl_add_u64 v[122:123], v[140:141], 1, v[122:123]
	v_mad_i64_i32 v[172:173], s[28:29], s24, v142, 0
	s_andn2_b64 vcc, exec, s[6:7]
	v_lshl_add_u64 v[172:173], v[172:173], 1, v[122:123]
	s_cbranch_vccnz .LBB0_705
	v_cvt_pk_bf16_f32 v178, v170, v171
	v_cvt_pk_bf16_f32 v179, v128, v129
	v_cvt_pk_bf16_f32 v180, v126, v127
	v_cvt_pk_bf16_f32 v181, v124, v125
	ds_bpermute_b32 v172, v252, v172
	ds_bpermute_b32 v173, v252, v173
	ds_bpermute_b32 v178, v252, v178
	ds_bpermute_b32 v179, v252, v179
	ds_bpermute_b32 v180, v252, v180
	ds_bpermute_b32 v181, v252, v181
	s_waitcnt lgkmcnt(0)
	global_store_dwordx4 v[172:173], v[178:181], off

.LBB0_707:
	s_andn2_b64 vcc, exec, s[0:1]
	s_cbranch_vccnz .LBB0_709
	v_cvt_pk_bf16_f32 v118, v118, v119
	v_cvt_pk_bf16_f32 v119, v120, v121
	v_cvt_pk_bf16_f32 v120, v114, v115
	v_cvt_pk_bf16_f32 v121, v116, v117
	ds_bpermute_b32 v118, v252, v118
	ds_bpermute_b32 v119, v252, v119
	ds_bpermute_b32 v120, v252, v120
	ds_bpermute_b32 v121, v252, v121
	s_waitcnt lgkmcnt(0)
	global_store_dwordx4 v[172:173], v[118:121], off offset:256

.LBB0_711:
	v_mad_i64_i32 v[106:107], s[6:7], s24, v118, 0
	s_andn2_b64 vcc, exec, s[0:1]
	v_lshl_add_u64 v[106:107], v[106:107], 1, v[122:123]
	s_cbranch_vccnz .LBB0_713
	v_cvt_pk_bf16_f32 v124, v116, v117
	v_cvt_pk_bf16_f32 v125, v112, v113
	v_cvt_pk_bf16_f32 v126, v110, v111
	v_cvt_pk_bf16_f32 v127, v108, v109
	ds_bpermute_b32 v106, v252, v106
	ds_bpermute_b32 v107, v252, v107
	ds_bpermute_b32 v124, v252, v124
	ds_bpermute_b32 v125, v252, v125
	ds_bpermute_b32 v126, v252, v126
	ds_bpermute_b32 v127, v252, v127
	s_waitcnt lgkmcnt(0)
	global_store_dwordx4 v[106:107], v[124:127], off

.LBB0_715:
	s_andn2_b64 vcc, exec, s[0:1]
	s_cbranch_vccnz .LBB0_717
	v_cvt_pk_bf16_f32 v102, v102, v103
	v_cvt_pk_bf16_f32 v103, v104, v105
	v_cvt_pk_bf16_f32 v104, v98, v99
	v_cvt_pk_bf16_f32 v105, v100, v101
	ds_bpermute_b32 v102, v252, v102
	ds_bpermute_b32 v103, v252, v103
	ds_bpermute_b32 v104, v252, v104
	ds_bpermute_b32 v105, v252, v105
	s_waitcnt lgkmcnt(0)
	global_store_dwordx4 v[106:107], v[102:105], off offset:256

.LBB0_719:
	v_mad_i64_i32 v[90:91], s[6:7], s24, v102, 0
	s_andn2_b64 vcc, exec, s[0:1]
	v_lshl_add_u64 v[90:91], v[90:91], 1, v[122:123]
	s_cbranch_vccnz .LBB0_721
	v_cvt_pk_bf16_f32 v104, v100, v101
	v_cvt_pk_bf16_f32 v105, v96, v97
	v_cvt_pk_bf16_f32 v106, v94, v95
	v_cvt_pk_bf16_f32 v107, v92, v93
	ds_bpermute_b32 v90, v252, v90
	ds_bpermute_b32 v91, v252, v91
	ds_bpermute_b32 v104, v252, v104
	ds_bpermute_b32 v105, v252, v105
	ds_bpermute_b32 v106, v252, v106
	ds_bpermute_b32 v107, v252, v107
	s_waitcnt lgkmcnt(0)
	global_store_dwordx4 v[90:91], v[104:107], off

.LBB0_723:
	s_andn2_b64 vcc, exec, s[0:1]
	s_cbranch_vccnz .LBB0_725
	v_cvt_pk_bf16_f32 v86, v86, v87
	v_cvt_pk_bf16_f32 v87, v88, v89
	v_cvt_pk_bf16_f32 v88, v82, v83
	v_cvt_pk_bf16_f32 v89, v84, v85
	ds_bpermute_b32 v86, v252, v86
	ds_bpermute_b32 v87, v252, v87
	ds_bpermute_b32 v88, v252, v88
	ds_bpermute_b32 v89, v252, v89
	s_waitcnt lgkmcnt(0)
	global_store_dwordx4 v[90:91], v[86:89], off offset:256

.LBB0_727:
	v_mad_i64_i32 v[74:75], s[6:7], s24, v86, 0
	s_andn2_b64 vcc, exec, s[0:1]
	v_lshl_add_u64 v[74:75], v[74:75], 1, v[122:123]
	s_cbranch_vccnz .LBB0_729
	v_cvt_pk_bf16_f32 v88, v84, v85
	v_cvt_pk_bf16_f32 v89, v80, v81
	v_cvt_pk_bf16_f32 v90, v78, v79
	v_cvt_pk_bf16_f32 v91, v76, v77
	ds_bpermute_b32 v74, v252, v74
	ds_bpermute_b32 v75, v252, v75
	ds_bpermute_b32 v88, v252, v88
	ds_bpermute_b32 v89, v252, v89
	ds_bpermute_b32 v90, v252, v90
	ds_bpermute_b32 v91, v252, v91
	s_waitcnt lgkmcnt(0)
	global_store_dwordx4 v[74:75], v[88:91], off

.LBB0_731:
	s_andn2_b64 vcc, exec, s[0:1]
	s_cbranch_vccnz .LBB0_733
	v_cvt_pk_bf16_f32 v70, v70, v71
	v_cvt_pk_bf16_f32 v71, v72, v73
	v_cvt_pk_bf16_f32 v72, v66, v67
	v_cvt_pk_bf16_f32 v73, v68, v69
	ds_bpermute_b32 v70, v252, v70
	ds_bpermute_b32 v71, v252, v71
	ds_bpermute_b32 v72, v252, v72
	ds_bpermute_b32 v73, v252, v73
	s_waitcnt lgkmcnt(0)
	global_store_dwordx4 v[74:75], v[70:73], off offset:256

.LBB0_735:
	v_mad_i64_i32 v[58:59], s[6:7], s24, v70, 0
	s_andn2_b64 vcc, exec, s[0:1]
	v_lshl_add_u64 v[58:59], v[58:59], 1, v[122:123]
	s_cbranch_vccnz .LBB0_737
	v_cvt_pk_bf16_f32 v72, v68, v69
	v_cvt_pk_bf16_f32 v73, v64, v65
	v_cvt_pk_bf16_f32 v74, v62, v63
	v_cvt_pk_bf16_f32 v75, v60, v61
	ds_bpermute_b32 v58, v252, v58
	ds_bpermute_b32 v59, v252, v59
	ds_bpermute_b32 v72, v252, v72
	ds_bpermute_b32 v73, v252, v73
	ds_bpermute_b32 v74, v252, v74
	ds_bpermute_b32 v75, v252, v75
	s_waitcnt lgkmcnt(0)
	global_store_dwordx4 v[58:59], v[72:75], off

.LBB0_739:
	s_andn2_b64 vcc, exec, s[0:1]
	s_cbranch_vccnz .LBB0_741
	v_cvt_pk_bf16_f32 v54, v54, v55
	v_cvt_pk_bf16_f32 v55, v56, v57
	v_cvt_pk_bf16_f32 v56, v50, v51
	v_cvt_pk_bf16_f32 v57, v52, v53
	ds_bpermute_b32 v54, v252, v54
	ds_bpermute_b32 v55, v252, v55
	ds_bpermute_b32 v56, v252, v56
	ds_bpermute_b32 v57, v252, v57
	s_waitcnt lgkmcnt(0)
	global_store_dwordx4 v[58:59], v[54:57], off offset:256

.LBB0_743:
	v_mad_i64_i32 v[42:43], s[6:7], s24, v54, 0
	s_andn2_b64 vcc, exec, s[0:1]
	v_lshl_add_u64 v[42:43], v[42:43], 1, v[122:123]
	s_cbranch_vccnz .LBB0_745
	v_cvt_pk_bf16_f32 v56, v52, v53
	v_cvt_pk_bf16_f32 v57, v48, v49
	v_cvt_pk_bf16_f32 v58, v46, v47
	v_cvt_pk_bf16_f32 v59, v44, v45
	ds_bpermute_b32 v42, v252, v42
	ds_bpermute_b32 v43, v252, v43
	ds_bpermute_b32 v56, v252, v56
	ds_bpermute_b32 v57, v252, v57
	ds_bpermute_b32 v58, v252, v58
	ds_bpermute_b32 v59, v252, v59
	s_waitcnt lgkmcnt(0)
	global_store_dwordx4 v[42:43], v[56:59], off

.LBB0_747:
	s_andn2_b64 vcc, exec, s[0:1]
	s_cbranch_vccnz .LBB0_749
	v_cvt_pk_bf16_f32 v38, v38, v39
	v_cvt_pk_bf16_f32 v39, v40, v41
	v_cvt_pk_bf16_f32 v40, v34, v35
	v_cvt_pk_bf16_f32 v41, v36, v37
	ds_bpermute_b32 v38, v252, v38
	ds_bpermute_b32 v39, v252, v39
	ds_bpermute_b32 v40, v252, v40
	ds_bpermute_b32 v41, v252, v41
	s_waitcnt lgkmcnt(0)
	global_store_dwordx4 v[42:43], v[38:41], off offset:256

.LBB0_751:
	v_mad_i64_i32 v[26:27], s[6:7], s24, v38, 0
	s_andn2_b64 vcc, exec, s[0:1]
	v_lshl_add_u64 v[26:27], v[26:27], 1, v[122:123]
	s_cbranch_vccnz .LBB0_753
	v_cvt_pk_bf16_f32 v40, v36, v37
	v_cvt_pk_bf16_f32 v41, v32, v33
	v_cvt_pk_bf16_f32 v42, v30, v31
	v_cvt_pk_bf16_f32 v43, v28, v29
	ds_bpermute_b32 v26, v252, v26
	ds_bpermute_b32 v27, v252, v27
	ds_bpermute_b32 v40, v252, v40
	ds_bpermute_b32 v41, v252, v41
	ds_bpermute_b32 v42, v252, v42
	ds_bpermute_b32 v43, v252, v43
	s_waitcnt lgkmcnt(0)
	global_store_dwordx4 v[26:27], v[40:43], off

.LBB0_755:
	s_andn2_b64 vcc, exec, s[0:1]
	s_cbranch_vccnz .LBB0_757
	v_cvt_pk_bf16_f32 v22, v22, v23
	v_cvt_pk_bf16_f32 v23, v24, v25
	v_cvt_pk_bf16_f32 v24, v18, v19
	v_cvt_pk_bf16_f32 v25, v20, v21
	ds_bpermute_b32 v22, v252, v22
	ds_bpermute_b32 v23, v252, v23
	ds_bpermute_b32 v24, v252, v24
	ds_bpermute_b32 v25, v252, v25
	s_waitcnt lgkmcnt(0)
	global_store_dwordx4 v[26:27], v[22:25], off offset:256

.LBB0_759:
	v_mad_i64_i32 v[10:11], s[6:7], s24, v22, 0
	s_andn2_b64 vcc, exec, s[0:1]
	v_lshl_add_u64 v[10:11], v[10:11], 1, v[122:123]
	s_cbranch_vccnz .LBB0_761
	v_cvt_pk_bf16_f32 v24, v20, v21
	v_cvt_pk_bf16_f32 v25, v16, v17
	v_cvt_pk_bf16_f32 v26, v14, v15
	v_cvt_pk_bf16_f32 v27, v12, v13
	ds_bpermute_b32 v10, v252, v10
	ds_bpermute_b32 v11, v252, v11
	ds_bpermute_b32 v24, v252, v24
	ds_bpermute_b32 v25, v252, v25
	ds_bpermute_b32 v26, v252, v26
	ds_bpermute_b32 v27, v252, v27
	s_waitcnt lgkmcnt(0)
	global_store_dwordx4 v[10:11], v[24:27], off

.LBB0_765:
	v_cvt_pk_bf16_f32 v6, v6, v7
	v_cvt_pk_bf16_f32 v7, v8, v9
	v_cvt_pk_bf16_f32 v8, v2, v3
	v_cvt_pk_bf16_f32 v9, v4, v5
	ds_bpermute_b32 v6, v252, v6
	ds_bpermute_b32 v7, v252, v7
	ds_bpermute_b32 v8, v252, v8
	ds_bpermute_b32 v9, v252, v9
	s_waitcnt lgkmcnt(0)
	global_store_dwordx4 v[10:11], v[6:9], off offset:256
	s_andn2_b64 vcc, exec, s[40:41]
	s_mov_b64 s[0:1], -1
	s_cbranch_vccnz .LBB0_694
